# proj GEMM epilogue stores (PH, QKV, gates: 285 MB) also use the nt cache policy
# baseline (speedup 1.0000x reference)
.LBB0_425:
	v_add_u32_e32 v176, s63, v205
	v_ashrrev_i32_e32 v177, 31, v176
	v_mul_lo_u32 v171, v171, s70
	v_mul_lo_u32 v189, v170, s71
	v_mad_u64_u32 v[202:203], s[2:3], v170, s70, 0
	v_lshl_add_u64 v[176:177], v[176:177], 1, s[48:49]
	v_add3_u32 v203, v203, v189, v171
	v_lshl_add_u64 v[202:203], v[202:203], 1, v[176:177]
	s_and_b64 vcc, exec, s[42:43]
	v_cvt_pk_bf16_f32 v156, v156, v157
	v_cvt_pk_bf16_f32 v157, v158, v159
	v_cvt_pk_bf16_f32 v158, v152, v153
	v_cvt_pk_bf16_f32 v159, v154, v155
	global_store_dwordx4 v[202:203], v[156:159], off nt
	s_cbranch_vccnz .LBB0_427
	v_pk_fma_f32 v[150:151], v[66:67], v[188:189], v[150:151] op_sel_hi:[1,0,1] neg_lo:[1,0,0] neg_hi:[1,0,0]
	v_pk_fma_f32 v[144:145], v[68:69], v[188:189], v[144:145] op_sel_hi:[1,0,1] neg_lo:[1,0,0] neg_hi:[1,0,0]
	v_pk_fma_f32 v[146:147], v[70:71], v[188:189], v[146:147] op_sel_hi:[1,0,1] neg_lo:[1,0,0] neg_hi:[1,0,0]
	v_pk_fma_f32 v[148:149], v[64:65], v[188:189], v[148:149] op_sel_hi:[1,0,1] neg_lo:[1,0,0] neg_hi:[1,0,0]
	v_pk_fma_f32 v[146:147], v[190:191], v[146:147], v[78:79] op_sel_hi:[0,1,1]
	v_pk_fma_f32 v[148:149], v[190:191], v[148:149], v[72:73] op_sel_hi:[0,1,1]
	v_pk_fma_f32 v[144:145], v[190:191], v[144:145], v[76:77] op_sel_hi:[0,1,1]
	v_pk_fma_f32 v[150:151], v[190:191], v[150:151], v[74:75] op_sel_hi:[0,1,1]

.LBB0_429:
	s_and_b64 vcc, exec, s[42:43]
	v_cvt_pk_bf16_f32 v148, v148, v149
	v_cvt_pk_bf16_f32 v149, v150, v151
	v_cvt_pk_bf16_f32 v150, v144, v145
	v_cvt_pk_bf16_f32 v151, v146, v147
	global_store_dwordx4 v[202:203], v[148:151], off offset:256 nt
	s_cbranch_vccnz .LBB0_431
	v_fma_f32 v144, -v186, v186, v187
	v_max_f32_e32 v144, 0, v144
	v_add_f32_e32 v144, 0x3727c5ac, v144
	v_mul_f32_e32 v145, 0x4b800000, v144
	v_cmp_gt_f32_e32 vcc, s13, v144
	s_nop 1
	v_cndmask_b32_e32 v144, v144, v145, vcc
	v_rsq_f32_e32 v144, v144
	s_nop 0
	v_mul_f32_e32 v145, 0x45800000, v144
	v_cndmask_b32_e32 v144, v144, v145, vcc
	s_and_b64 vcc, exec, s[42:43]
	s_cbranch_vccz .LBB0_432
	s_branch .LBB0_433

.LBB0_435:
	v_add_u32_e32 v145, 16, v170
	v_ashrrev_i32_e32 v146, 31, v145
	v_mul_lo_u32 v148, s70, v146
	v_mul_lo_u32 v149, s71, v145
	v_mad_u64_u32 v[146:147], s[2:3], s70, v145, 0
	v_add3_u32 v147, v147, v148, v149
	v_lshl_add_u64 v[146:147], v[146:147], 1, v[176:177]
	s_and_b64 vcc, exec, s[42:43]
	v_cvt_pk_bf16_f32 v140, v140, v141
	v_cvt_pk_bf16_f32 v141, v142, v143
	v_cvt_pk_bf16_f32 v142, v136, v137
	v_cvt_pk_bf16_f32 v143, v138, v139
	global_store_dwordx4 v[146:147], v[140:143], off nt
	s_cbranch_vccnz .LBB0_437
	v_pk_fma_f32 v[134:135], v[66:67], v[186:187], v[134:135] op_sel_hi:[1,0,1] neg_lo:[1,0,0] neg_hi:[1,0,0]
	v_pk_fma_f32 v[128:129], v[68:69], v[186:187], v[128:129] op_sel_hi:[1,0,1] neg_lo:[1,0,0] neg_hi:[1,0,0]
	v_pk_fma_f32 v[130:131], v[70:71], v[186:187], v[130:131] op_sel_hi:[1,0,1] neg_lo:[1,0,0] neg_hi:[1,0,0]
	v_pk_fma_f32 v[132:133], v[64:65], v[186:187], v[132:133] op_sel_hi:[1,0,1] neg_lo:[1,0,0] neg_hi:[1,0,0]
	v_pk_fma_f32 v[130:131], v[144:145], v[130:131], v[78:79] op_sel_hi:[0,1,1]
	v_pk_fma_f32 v[132:133], v[144:145], v[132:133], v[72:73] op_sel_hi:[0,1,1]
	v_pk_fma_f32 v[128:129], v[144:145], v[128:129], v[76:77] op_sel_hi:[0,1,1]
	v_pk_fma_f32 v[134:135], v[144:145], v[134:135], v[74:75] op_sel_hi:[0,1,1]

.LBB0_439:
	s_and_b64 vcc, exec, s[42:43]
	v_cvt_pk_bf16_f32 v132, v132, v133
	v_cvt_pk_bf16_f32 v133, v134, v135
	v_cvt_pk_bf16_f32 v134, v128, v129
	v_cvt_pk_bf16_f32 v135, v130, v131
	global_store_dwordx4 v[146:147], v[132:135], off offset:256 nt
	s_cbranch_vccnz .LBB0_441
	v_fma_f32 v128, -v184, v184, v185
	v_max_f32_e32 v128, 0, v128
	v_add_f32_e32 v128, 0x3727c5ac, v128
	v_mul_f32_e32 v129, 0x4b800000, v128
	v_cmp_gt_f32_e32 vcc, s13, v128
	s_nop 1
	v_cndmask_b32_e32 v128, v128, v129, vcc
	v_rsq_f32_e32 v128, v128
	s_nop 0
	v_mul_f32_e32 v129, 0x45800000, v128
	v_cndmask_b32_e32 v128, v128, v129, vcc
	s_and_b64 vcc, exec, s[42:43]
	s_cbranch_vccz .LBB0_442
	s_branch .LBB0_443

.LBB0_445:
	v_add_u32_e32 v129, 32, v170
	v_ashrrev_i32_e32 v130, 31, v129
	v_mul_lo_u32 v132, s70, v130
	v_mul_lo_u32 v133, s71, v129
	v_mad_u64_u32 v[130:131], s[2:3], s70, v129, 0
	v_add3_u32 v131, v131, v132, v133
	v_lshl_add_u64 v[130:131], v[130:131], 1, v[176:177]
	s_and_b64 vcc, exec, s[42:43]
	v_cvt_pk_bf16_f32 v124, v124, v125
	v_cvt_pk_bf16_f32 v125, v126, v127
	v_cvt_pk_bf16_f32 v126, v120, v121
	v_cvt_pk_bf16_f32 v127, v122, v123
	global_store_dwordx4 v[130:131], v[124:127], off nt
	s_cbranch_vccnz .LBB0_447
	v_pk_fma_f32 v[118:119], v[66:67], v[184:185], v[118:119] op_sel_hi:[1,0,1] neg_lo:[1,0,0] neg_hi:[1,0,0]
	v_pk_fma_f32 v[112:113], v[68:69], v[184:185], v[112:113] op_sel_hi:[1,0,1] neg_lo:[1,0,0] neg_hi:[1,0,0]
	v_pk_fma_f32 v[114:115], v[70:71], v[184:185], v[114:115] op_sel_hi:[1,0,1] neg_lo:[1,0,0] neg_hi:[1,0,0]
	v_pk_fma_f32 v[116:117], v[64:65], v[184:185], v[116:117] op_sel_hi:[1,0,1] neg_lo:[1,0,0] neg_hi:[1,0,0]
	v_pk_fma_f32 v[114:115], v[128:129], v[114:115], v[78:79] op_sel_hi:[0,1,1]
	v_pk_fma_f32 v[116:117], v[128:129], v[116:117], v[72:73] op_sel_hi:[0,1,1]
	v_pk_fma_f32 v[112:113], v[128:129], v[112:113], v[76:77] op_sel_hi:[0,1,1]
	v_pk_fma_f32 v[118:119], v[128:129], v[118:119], v[74:75] op_sel_hi:[0,1,1]

.LBB0_449:
	s_and_b64 vcc, exec, s[42:43]
	v_cvt_pk_bf16_f32 v116, v116, v117
	v_cvt_pk_bf16_f32 v117, v118, v119
	v_cvt_pk_bf16_f32 v118, v112, v113
	v_cvt_pk_bf16_f32 v119, v114, v115
	global_store_dwordx4 v[130:131], v[116:119], off offset:256 nt
	s_cbranch_vccnz .LBB0_451
	v_fma_f32 v112, -v182, v182, v183
	v_max_f32_e32 v112, 0, v112
	v_add_f32_e32 v112, 0x3727c5ac, v112
	v_mul_f32_e32 v113, 0x4b800000, v112
	v_cmp_gt_f32_e32 vcc, s13, v112
	s_nop 1
	v_cndmask_b32_e32 v112, v112, v113, vcc
	v_rsq_f32_e32 v112, v112
	s_nop 0
	v_mul_f32_e32 v113, 0x45800000, v112
	v_cndmask_b32_e32 v112, v112, v113, vcc
	s_and_b64 vcc, exec, s[42:43]
	s_cbranch_vccz .LBB0_452
	s_branch .LBB0_453

.LBB0_455:
	v_add_u32_e32 v113, 48, v170
	v_ashrrev_i32_e32 v114, 31, v113
	v_mul_lo_u32 v116, s70, v114
	v_mul_lo_u32 v117, s71, v113
	v_mad_u64_u32 v[114:115], s[2:3], s70, v113, 0
	v_add3_u32 v115, v115, v116, v117
	v_lshl_add_u64 v[114:115], v[114:115], 1, v[176:177]
	s_and_b64 vcc, exec, s[42:43]
	v_cvt_pk_bf16_f32 v108, v108, v109
	v_cvt_pk_bf16_f32 v109, v110, v111
	v_cvt_pk_bf16_f32 v110, v104, v105
	v_cvt_pk_bf16_f32 v111, v106, v107
	global_store_dwordx4 v[114:115], v[108:111], off nt
	s_cbranch_vccnz .LBB0_457
	v_pk_fma_f32 v[102:103], v[66:67], v[182:183], v[102:103] op_sel_hi:[1,0,1] neg_lo:[1,0,0] neg_hi:[1,0,0]
	v_pk_fma_f32 v[80:81], v[68:69], v[182:183], v[80:81] op_sel_hi:[1,0,1] neg_lo:[1,0,0] neg_hi:[1,0,0]
	v_pk_fma_f32 v[82:83], v[70:71], v[182:183], v[82:83] op_sel_hi:[1,0,1] neg_lo:[1,0,0] neg_hi:[1,0,0]
	v_pk_fma_f32 v[100:101], v[64:65], v[182:183], v[100:101] op_sel_hi:[1,0,1] neg_lo:[1,0,0] neg_hi:[1,0,0]
	v_pk_fma_f32 v[82:83], v[112:113], v[82:83], v[78:79] op_sel_hi:[0,1,1]
	v_pk_fma_f32 v[100:101], v[112:113], v[100:101], v[72:73] op_sel_hi:[0,1,1]
	v_pk_fma_f32 v[80:81], v[112:113], v[80:81], v[76:77] op_sel_hi:[0,1,1]
	v_pk_fma_f32 v[102:103], v[112:113], v[102:103], v[74:75] op_sel_hi:[0,1,1]

.LBB0_459:
	s_and_b64 vcc, exec, s[42:43]
	v_cvt_pk_bf16_f32 v100, v100, v101
	v_cvt_pk_bf16_f32 v101, v102, v103
	v_cvt_pk_bf16_f32 v102, v80, v81
	v_cvt_pk_bf16_f32 v103, v82, v83
	global_store_dwordx4 v[114:115], v[100:103], off offset:256 nt
	s_cbranch_vccnz .LBB0_461
	v_fma_f32 v80, -v180, v180, v181
	v_max_f32_e32 v80, 0, v80
	v_add_f32_e32 v80, 0x3727c5ac, v80
	v_mul_f32_e32 v81, 0x4b800000, v80
	v_cmp_gt_f32_e32 vcc, s13, v80
	s_nop 1
	v_cndmask_b32_e32 v80, v80, v81, vcc
	v_rsq_f32_e32 v80, v80
	s_nop 0
	v_mul_f32_e32 v81, 0x45800000, v80
	v_cndmask_b32_e32 v80, v80, v81, vcc
	s_and_b64 vcc, exec, s[42:43]
	s_cbranch_vccz .LBB0_462
	s_branch .LBB0_463

.LBB0_465:
	v_add_u32_e32 v81, 0x80, v170
	v_ashrrev_i32_e32 v82, 31, v81
	v_mul_lo_u32 v100, s70, v82
	v_mul_lo_u32 v101, s71, v81
	v_mad_u64_u32 v[82:83], s[2:3], s70, v81, 0
	v_add3_u32 v83, v83, v100, v101
	v_lshl_add_u64 v[82:83], v[82:83], 1, v[176:177]
	s_and_b64 vcc, exec, s[42:43]
	v_cvt_pk_bf16_f32 v60, v60, v61
	v_cvt_pk_bf16_f32 v61, v62, v63
	v_cvt_pk_bf16_f32 v62, v56, v57
	v_cvt_pk_bf16_f32 v63, v58, v59
	global_store_dwordx4 v[82:83], v[60:63], off nt
	s_cbranch_vccnz .LBB0_467
	v_pk_fma_f32 v[54:55], v[66:67], v[180:181], v[54:55] op_sel_hi:[1,0,1] neg_lo:[1,0,0] neg_hi:[1,0,0]
	v_pk_fma_f32 v[48:49], v[68:69], v[180:181], v[48:49] op_sel_hi:[1,0,1] neg_lo:[1,0,0] neg_hi:[1,0,0]
	v_pk_fma_f32 v[50:51], v[70:71], v[180:181], v[50:51] op_sel_hi:[1,0,1] neg_lo:[1,0,0] neg_hi:[1,0,0]
	v_pk_fma_f32 v[52:53], v[64:65], v[180:181], v[52:53] op_sel_hi:[1,0,1] neg_lo:[1,0,0] neg_hi:[1,0,0]
	v_pk_fma_f32 v[50:51], v[80:81], v[50:51], v[78:79] op_sel_hi:[0,1,1]
	v_pk_fma_f32 v[52:53], v[80:81], v[52:53], v[72:73] op_sel_hi:[0,1,1]
	v_pk_fma_f32 v[48:49], v[80:81], v[48:49], v[76:77] op_sel_hi:[0,1,1]
	v_pk_fma_f32 v[54:55], v[80:81], v[54:55], v[74:75] op_sel_hi:[0,1,1]

.LBB0_469:
	s_and_b64 vcc, exec, s[42:43]
	v_cvt_pk_bf16_f32 v52, v52, v53
	v_cvt_pk_bf16_f32 v53, v54, v55
	v_cvt_pk_bf16_f32 v54, v48, v49
	v_cvt_pk_bf16_f32 v55, v50, v51
	global_store_dwordx4 v[82:83], v[52:55], off offset:256 nt
	s_cbranch_vccnz .LBB0_471
	v_fma_f32 v48, -v178, v178, v179
	v_max_f32_e32 v48, 0, v48
	v_add_f32_e32 v48, 0x3727c5ac, v48
	v_mul_f32_e32 v49, 0x4b800000, v48
	v_cmp_gt_f32_e32 vcc, s13, v48
	s_nop 1
	v_cndmask_b32_e32 v48, v48, v49, vcc
	v_rsq_f32_e32 v48, v48
	s_nop 0
	v_mul_f32_e32 v49, 0x45800000, v48
	v_cndmask_b32_e32 v48, v48, v49, vcc
	s_and_b64 vcc, exec, s[42:43]
	s_cbranch_vccz .LBB0_472
	s_branch .LBB0_473

.LBB0_475:
	v_add_u32_e32 v49, 0x90, v170
	v_ashrrev_i32_e32 v50, 31, v49
	v_mul_lo_u32 v52, s70, v50
	v_mul_lo_u32 v53, s71, v49
	v_mad_u64_u32 v[50:51], s[2:3], s70, v49, 0
	v_add3_u32 v51, v51, v52, v53
	v_lshl_add_u64 v[50:51], v[50:51], 1, v[176:177]
	s_and_b64 vcc, exec, s[42:43]
	v_cvt_pk_bf16_f32 v44, v44, v45
	v_cvt_pk_bf16_f32 v45, v46, v47
	v_cvt_pk_bf16_f32 v46, v40, v41
	v_cvt_pk_bf16_f32 v47, v42, v43
	global_store_dwordx4 v[50:51], v[44:47], off nt
	s_cbranch_vccnz .LBB0_477
	v_pk_fma_f32 v[38:39], v[66:67], v[178:179], v[38:39] op_sel_hi:[1,0,1] neg_lo:[1,0,0] neg_hi:[1,0,0]
	v_pk_fma_f32 v[32:33], v[68:69], v[178:179], v[32:33] op_sel_hi:[1,0,1] neg_lo:[1,0,0] neg_hi:[1,0,0]
	v_pk_fma_f32 v[34:35], v[70:71], v[178:179], v[34:35] op_sel_hi:[1,0,1] neg_lo:[1,0,0] neg_hi:[1,0,0]
	v_pk_fma_f32 v[36:37], v[64:65], v[178:179], v[36:37] op_sel_hi:[1,0,1] neg_lo:[1,0,0] neg_hi:[1,0,0]
	v_pk_fma_f32 v[34:35], v[48:49], v[34:35], v[78:79] op_sel_hi:[0,1,1]
	v_pk_fma_f32 v[36:37], v[48:49], v[36:37], v[72:73] op_sel_hi:[0,1,1]
	v_pk_fma_f32 v[32:33], v[48:49], v[32:33], v[76:77] op_sel_hi:[0,1,1]
	v_pk_fma_f32 v[38:39], v[48:49], v[38:39], v[74:75] op_sel_hi:[0,1,1]

.LBB0_479:
	s_and_b64 vcc, exec, s[42:43]
	v_cvt_pk_bf16_f32 v36, v36, v37
	v_cvt_pk_bf16_f32 v37, v38, v39
	v_cvt_pk_bf16_f32 v38, v32, v33
	v_cvt_pk_bf16_f32 v39, v34, v35
	global_store_dwordx4 v[50:51], v[36:39], off offset:256 nt
	s_cbranch_vccnz .LBB0_481
	v_fma_f32 v32, -v174, v174, v175
	v_max_f32_e32 v32, 0, v32
	v_add_f32_e32 v32, 0x3727c5ac, v32
	v_mul_f32_e32 v33, 0x4b800000, v32
	v_cmp_gt_f32_e32 vcc, s13, v32
	s_nop 1
	v_cndmask_b32_e32 v32, v32, v33, vcc
	v_rsq_f32_e32 v32, v32
	s_nop 0
	v_mul_f32_e32 v33, 0x45800000, v32
	v_cndmask_b32_e32 v32, v32, v33, vcc
	s_and_b64 vcc, exec, s[42:43]
	s_cbranch_vccz .LBB0_482
	s_branch .LBB0_483

.LBB0_485:
	v_add_u32_e32 v33, 0xa0, v170
	v_ashrrev_i32_e32 v34, 31, v33
	v_mul_lo_u32 v36, s70, v34
	v_mul_lo_u32 v37, s71, v33
	v_mad_u64_u32 v[34:35], s[2:3], s70, v33, 0
	v_add3_u32 v35, v35, v36, v37
	v_lshl_add_u64 v[34:35], v[34:35], 1, v[176:177]
	s_and_b64 vcc, exec, s[42:43]
	v_cvt_pk_bf16_f32 v28, v28, v29
	v_cvt_pk_bf16_f32 v29, v30, v31
	v_cvt_pk_bf16_f32 v30, v24, v25
	v_cvt_pk_bf16_f32 v31, v26, v27
	global_store_dwordx4 v[34:35], v[28:31], off nt
	s_cbranch_vccnz .LBB0_487
	v_pk_fma_f32 v[22:23], v[66:67], v[174:175], v[22:23] op_sel_hi:[1,0,1] neg_lo:[1,0,0] neg_hi:[1,0,0]
	v_pk_fma_f32 v[16:17], v[68:69], v[174:175], v[16:17] op_sel_hi:[1,0,1] neg_lo:[1,0,0] neg_hi:[1,0,0]
	v_pk_fma_f32 v[18:19], v[70:71], v[174:175], v[18:19] op_sel_hi:[1,0,1] neg_lo:[1,0,0] neg_hi:[1,0,0]
	v_pk_fma_f32 v[20:21], v[64:65], v[174:175], v[20:21] op_sel_hi:[1,0,1] neg_lo:[1,0,0] neg_hi:[1,0,0]
	v_pk_fma_f32 v[18:19], v[32:33], v[18:19], v[78:79] op_sel_hi:[0,1,1]
	v_pk_fma_f32 v[20:21], v[32:33], v[20:21], v[72:73] op_sel_hi:[0,1,1]
	v_pk_fma_f32 v[16:17], v[32:33], v[16:17], v[76:77] op_sel_hi:[0,1,1]
	v_pk_fma_f32 v[22:23], v[32:33], v[22:23], v[74:75] op_sel_hi:[0,1,1]

.LBB0_489:
	s_and_b64 vcc, exec, s[42:43]
	v_cvt_pk_bf16_f32 v20, v20, v21
	v_cvt_pk_bf16_f32 v21, v22, v23
	v_cvt_pk_bf16_f32 v22, v16, v17
	v_cvt_pk_bf16_f32 v23, v18, v19
	global_store_dwordx4 v[34:35], v[20:23], off offset:256 nt
	s_cbranch_vccnz .LBB0_491
	v_fma_f32 v16, -v172, v172, v173
	v_max_f32_e32 v16, 0, v16
	v_add_f32_e32 v16, 0x3727c5ac, v16
	v_mul_f32_e32 v17, 0x4b800000, v16
	v_cmp_gt_f32_e32 vcc, s13, v16
	s_nop 1
	v_cndmask_b32_e32 v16, v16, v17, vcc
	v_rsq_f32_e32 v16, v16
	s_nop 0
	v_mul_f32_e32 v17, 0x45800000, v16
	v_cndmask_b32_e32 v16, v16, v17, vcc
	s_and_b64 vcc, exec, s[42:43]
	s_cbranch_vccz .LBB0_492
	s_branch .LBB0_493

.LBB0_495:
	v_add_u32_e32 v17, 0xb0, v170
	v_ashrrev_i32_e32 v18, 31, v17
	v_mul_lo_u32 v20, s70, v18
	v_mul_lo_u32 v21, s71, v17
	v_mad_u64_u32 v[18:19], s[2:3], s70, v17, 0
	v_add3_u32 v19, v19, v20, v21
	v_lshl_add_u64 v[18:19], v[18:19], 1, v[176:177]
	s_and_b64 vcc, exec, s[42:43]
	v_cvt_pk_bf16_f32 v12, v12, v13
	v_cvt_pk_bf16_f32 v13, v14, v15
	v_cvt_pk_bf16_f32 v14, v8, v9
	v_cvt_pk_bf16_f32 v15, v10, v11
	global_store_dwordx4 v[18:19], v[12:15], off nt
	s_cbranch_vccnz .LBB0_497
	v_pk_fma_f32 v[6:7], v[66:67], v[172:173], v[6:7] op_sel_hi:[1,0,1] neg_lo:[1,0,0] neg_hi:[1,0,0]
	v_pk_fma_f32 v[0:1], v[68:69], v[172:173], v[0:1] op_sel_hi:[1,0,1] neg_lo:[1,0,0] neg_hi:[1,0,0]
	v_pk_fma_f32 v[2:3], v[70:71], v[172:173], v[2:3] op_sel_hi:[1,0,1] neg_lo:[1,0,0] neg_hi:[1,0,0]
	v_pk_fma_f32 v[4:5], v[64:65], v[172:173], v[4:5] op_sel_hi:[1,0,1] neg_lo:[1,0,0] neg_hi:[1,0,0]
	v_pk_fma_f32 v[2:3], v[16:17], v[2:3], v[78:79] op_sel_hi:[0,1,1]
	v_pk_fma_f32 v[4:5], v[16:17], v[4:5], v[72:73] op_sel_hi:[0,1,1]
	v_pk_fma_f32 v[0:1], v[16:17], v[0:1], v[76:77] op_sel_hi:[0,1,1]
	v_pk_fma_f32 v[6:7], v[16:17], v[6:7], v[74:75] op_sel_hi:[0,1,1]

.LBB0_504:
	s_add_i32 s2, s4, 0x80
	s_cmpk_lt_i32 s4, 0x480
	s_mov_b32 s4, s2
	s_waitcnt lgkmcnt(0)
	global_store_dwordx4 v[30:31], v[12:15], off offset:48 nt
	s_cbranch_scc0 .LBB0_511
